# weight-transpose tiles: the 16 row loads of a tile are issued up front (cache warm) instead of 1-2 loads per vmcnt drain
# speedup vs baseline: 1.0345x; 1.0345x over previous
; DEVINL void tr_tile(const Params& p, char* smem, int kind, int nt, int kt) {
;     ...
;     src = p.w_down; ld = 1024; col = n; K = DFF; dst = (u16*)(p.ws + OFF_WDT);
;   }
;   __syncthreads();
; #pragma unroll 4
;   for (int i = 0; i < 16; ++i) {
;     int k = kq * 16 + i;
;     float v = valid ? src[(size_t)(k0 + k) * ld + col] : 0.f;
;     if (ksc) v *= ksc[k0 + k];
;     if (kind == 2 && (k0 + k) >= 512) v *= p.s5_norm[k0 + k - 512];
;     T[k * 65 + nl] = v * cs;
;   }
.LBB0_238:
	s_movk_i32 s0, 0x57f
	v_cmp_lt_i32_e32 vcc, s0, v16
	s_and_saveexec_b64 s[0:1], vcc
	s_xor_b64 s[34:35], exec, s[0:1]
	s_cbranch_execz .LBB0_242
	v_add_u16_e32 v1, 0xfa80, v16
	v_mul_u32_u24_e32 v3, 0xba2f, v1
	v_lshrrev_b32_e32 v3, 21, v3
	s_waitcnt lgkmcnt(0)
	v_mul_lo_u16_e32 v4, 44, v3
	v_sub_u16_e32 v1, v1, v4
	v_mov_b32_e32 v7, v0
	v_lshlrev_b32_e32 v13, 6, v3
	v_lshlrev_b16_e32 v12, 6, v1
	v_and_b32_e32 v1, 63, v7
	v_or_b32_e32 v3, v1, v13
	v_ashrrev_i32_e32 v15, 2, v7
	v_readlane_b32 s40, v194, 1
	v_lshlrev_b32_e32 v4, 2, v3
	s_waitcnt lgkmcnt(0)
	v_mov_b32_e32 v5, v2
	v_readlane_b32 s44, v194, 5
	v_readlane_b32 s45, v194, 6
	v_and_b32_e32 v8, -16, v15
	v_lshlrev_b32_e32 v6, 2, v1
	v_lshl_add_u64 v[4:5], s[44:45], 0, v[4:5]
	v_mov_b32_e32 v1, v12
	v_mov_b32_e32 v3, v8
	s_mov_b32 s0, 1
	s_mov_b32 s1, 0
	s_mov_b32 s40, 16
	s_barrier
	v_readlane_b32 s41, v194, 2
	v_readlane_b32 s42, v194, 3
	v_readlane_b32 s43, v194, 4
	v_readlane_b32 s46, v194, 7
	v_readlane_b32 s47, v194, 8
	v_add_u32_e32 v206, v8, v12
	v_ashrrev_i32_e32 v207, 31, v206
	v_lshlrev_b64 v[206:207], 12, v[206:207]
	v_lshl_add_u64 v[206:207], v[4:5], 0, v[206:207]
	s_mov_b64 s[100:101], 0x1000
	global_load_dword v204, v[206:207], off
	v_lshl_add_u64 v[206:207], v[206:207], 0, s[100:101]
	global_load_dword v204, v[206:207], off
	v_lshl_add_u64 v[206:207], v[206:207], 0, s[100:101]
	global_load_dword v204, v[206:207], off
	v_lshl_add_u64 v[206:207], v[206:207], 0, s[100:101]
	global_load_dword v204, v[206:207], off
	v_lshl_add_u64 v[206:207], v[206:207], 0, s[100:101]
	global_load_dword v204, v[206:207], off
	v_lshl_add_u64 v[206:207], v[206:207], 0, s[100:101]
	global_load_dword v204, v[206:207], off
	v_lshl_add_u64 v[206:207], v[206:207], 0, s[100:101]
	global_load_dword v204, v[206:207], off
	v_lshl_add_u64 v[206:207], v[206:207], 0, s[100:101]
	global_load_dword v204, v[206:207], off
	v_lshl_add_u64 v[206:207], v[206:207], 0, s[100:101]
	global_load_dword v204, v[206:207], off
	v_lshl_add_u64 v[206:207], v[206:207], 0, s[100:101]
	global_load_dword v204, v[206:207], off
	v_lshl_add_u64 v[206:207], v[206:207], 0, s[100:101]
	global_load_dword v204, v[206:207], off
	v_lshl_add_u64 v[206:207], v[206:207], 0, s[100:101]
	global_load_dword v204, v[206:207], off
	v_lshl_add_u64 v[206:207], v[206:207], 0, s[100:101]
	global_load_dword v204, v[206:207], off
	v_lshl_add_u64 v[206:207], v[206:207], 0, s[100:101]
	global_load_dword v204, v[206:207], off
	v_lshl_add_u64 v[206:207], v[206:207], 0, s[100:101]
	global_load_dword v204, v[206:207], off
	v_lshl_add_u64 v[206:207], v[206:207], 0, s[100:101]
	global_load_dword v204, v[206:207], off

; DEVINL void tr_tile(const Params& p, char* smem, int kind, int nt, int kt) {
;     ...
;     int Tt = n >> 7, loc = n & 127, wn = loc >> 6, nf = (loc >> 4) & 3, c = loc & 15;
;     int hidden = Tt * 64 + wn * 32 + (nf & 1) * 16 + c;
;     src = (nf >= 2) ? p.w_up : p.w_gate; ld = DFF; col = hidden; ksc = p.g_pre_ffn; dst = (u16*)(p.ws + OFF_WGUT);
;   } else {
;     src = p.w_down; ld = 1024; col = n; K = DFF; dst = (u16*)(p.ws + OFF_WDT);
;   }
;   __syncthreads();
; #pragma unroll 4
;   for (int i = 0; i < 16; ++i) {
;     int k = kq * 16 + i;
;     float v = valid ? src[(size_t)(k0 + k) * ld + col] : 0.f;
;     if (ksc) v *= ksc[k0 + k];
;     if (kind == 2 && (k0 + k) >= 512) v *= p.s5_norm[k0 + k - 512];
;     T[k * 65 + nl] = v * cs;
.LBB0_242:
	s_andn2_saveexec_b64 s[40:41], s[34:35]
	s_cbranch_execz .LBB0_237
	v_ashrrev_i32_e32 v1, 31, v16
	v_lshrrev_b32_e32 v1, 28, v1
	v_add_u32_e32 v3, v16, v1
	v_ashrrev_i32_e32 v1, 4, v3
	v_and_b32_e32 v3, 0x3fffff0, v3
	s_mov_b64 s[44:45], s[84:85]
	v_sub_u32_e32 v3, v16, v3
	v_mov_b32_e32 v14, v0
	v_readlane_b32 s84, v194, 1
	v_lshlrev_b32_e32 v12, 6, v3
	v_and_b32_e32 v3, 32, v14
	v_readlane_b32 s85, v194, 2
	v_readlane_b32 s87, v194, 4
	v_readlane_b32 s86, v194, 3
	s_waitcnt lgkmcnt(0)
	v_mov_b32_e32 v5, s85
	v_mov_b32_e32 v4, s87
	v_cmp_eq_u32_e32 vcc, 0, v3
	v_mov_b32_e32 v3, s86
	v_ashrrev_i32_e32 v13, 31, v12
	v_cndmask_b32_e32 v7, v4, v5, vcc
	v_mov_b32_e32 v4, s84
	v_cndmask_b32_e32 v6, v3, v4, vcc
	v_ashrrev_i32_e32 v3, 2, v14
	v_and_b32_e32 v8, -16, v3
	v_ashrrev_i32_e32 v9, 31, v8
	v_lshl_add_u64 v[4:5], v[8:9], 0, v[12:13]
	v_lshrrev_b32_e32 v9, 4, v3
	s_movk_i32 s0, 0x1040
	v_and_b32_e32 v10, 63, v14
	v_and_b32_e32 v11, 31, v14
	v_mul_lo_u32 v9, v9, s0
	v_lshl_add_u32 v15, v10, 2, v9
	v_lshl_or_b32 v10, v1, 5, v11
	v_lshl_add_u32 v8, v16, 6, v8
	v_lshlrev_b32_e32 v9, 10, v1
	v_ashrrev_i32_e32 v11, 31, v10
	v_sub_u32_e32 v8, v8, v9
	v_lshlrev_b64 v[10:11], 2, v[10:11]
	s_movk_i32 s0, 0x2c00
	v_mad_i64_i32 v[10:11], s[0:1], v8, s0, v[10:11]
	v_ashrrev_i32_e32 v9, 31, v8
	v_lshl_add_u64 v[6:7], v[6:7], 0, v[10:11]
	s_mov_b64 s[0:1], 0x8400
	v_lshl_add_u64 v[4:5], v[4:5], 2, s[18:19]
	v_lshl_add_u64 v[6:7], v[6:7], 0, s[0:1]
	v_lshl_add_u64 v[8:9], v[8:9], 2, s[18:19]
	s_mov_b64 s[42:43], 0
	v_readlane_b32 s88, v194, 5
	v_readlane_b32 s89, v194, 6
	v_readlane_b32 s90, v194, 7
	v_readlane_b32 s91, v194, 8
	s_barrier
	s_mov_b32 s100, 0xffff7c00
	s_mov_b32 s101, -1
	v_lshl_add_u64 v[206:207], v[6:7], 0, s[100:101]
	s_mov_b64 s[100:101], 0x2c00
	global_load_dword v204, v[206:207], off
	v_lshl_add_u64 v[206:207], v[206:207], 0, s[100:101]
	global_load_dword v204, v[206:207], off
	v_lshl_add_u64 v[206:207], v[206:207], 0, s[100:101]
	global_load_dword v204, v[206:207], off
	v_lshl_add_u64 v[206:207], v[206:207], 0, s[100:101]
	global_load_dword v204, v[206:207], off
	v_lshl_add_u64 v[206:207], v[206:207], 0, s[100:101]
	global_load_dword v204, v[206:207], off
	v_lshl_add_u64 v[206:207], v[206:207], 0, s[100:101]
	global_load_dword v204, v[206:207], off
	v_lshl_add_u64 v[206:207], v[206:207], 0, s[100:101]
	global_load_dword v204, v[206:207], off
	v_lshl_add_u64 v[206:207], v[206:207], 0, s[100:101]
	global_load_dword v204, v[206:207], off
	v_lshl_add_u64 v[206:207], v[206:207], 0, s[100:101]
	global_load_dword v204, v[206:207], off
	v_lshl_add_u64 v[206:207], v[206:207], 0, s[100:101]
	global_load_dword v204, v[206:207], off
	v_lshl_add_u64 v[206:207], v[206:207], 0, s[100:101]
	global_load_dword v204, v[206:207], off
	v_lshl_add_u64 v[206:207], v[206:207], 0, s[100:101]
	global_load_dword v204, v[206:207], off
	v_lshl_add_u64 v[206:207], v[206:207], 0, s[100:101]
	global_load_dword v204, v[206:207], off
	v_lshl_add_u64 v[206:207], v[206:207], 0, s[100:101]
	global_load_dword v204, v[206:207], off
	v_lshl_add_u64 v[206:207], v[206:207], 0, s[100:101]
	global_load_dword v204, v[206:207], off
	v_lshl_add_u64 v[206:207], v[206:207], 0, s[100:101]
	global_load_dword v204, v[206:207], off
	s_branch .LBB0_245

; DEVINL int tidx() { int t = threadIdx.x; asm volatile("" : "+v"(t)); return t; }
; DEVINL float logsigf_(float z) { return fminf(z, 0.f) - __logf(1.f + __expf(-fabsf(z))); }
; DEVINL void gla_prep(const Params& p, char* smem, int r0, int T, int h, float (&bcum)[16]) {
;   float* gkl = (float*)(smem + G_GKL); float* Bc = (float*)(smem + G_BC);
;   float* tot = (float*)(smem + G_TOT); float* bl = (float*)(smem + G_BL);
;   const int tid = tidx(), lane = tid & 63, w = tid >> 6;
;   const float* gk = (const float*)(p.ws + OFF_GK);
;   __syncthreads();
;   {
;     int t = tid >> 2, c4 = (tid & 3) * 4;
;     const float4 v = *(const float4*)(gk + (size_t)(r0 + t) * 16 + c4);
;     *(float4*)(gkl + t * 16 + c4) = v;
;   }
;   float wreg[16];
; #pragma unroll
;   for (int r = 0; r < 16; ++r) wreg[r] = p.w_gk2[r * 256 + h * 64 + lane];
;   const float bias = p.b_gk[h * 64 + lane];
;   __syncthreads();
;   float run = 0.f;
; #pragma unroll
;   for (int i = 0; i < 16; ++i) {
;     const int t = 16 * w + i;
;     float z = bias;
; #pragma unroll
;     for (int r4 = 0; r4 < 4; ++r4) {
;       float4 gv = *(const float4*)(gkl + t * 16 + r4 * 4);
;       z += gv.x * wreg[r4 * 4] + gv.y * wreg[r4 * 4 + 1] + gv.z * wreg[r4 * 4 + 2] + gv.w * wreg[r4 * 4 + 3];
;     }
;     float lg = (t < T) ? logsigf_(z) * (1.f / 16.f) : 0.f;
; DEVINL void gla_passA(const Params& p, char* smem, int item) {
;     ...
;   for (int ks = 0; ks < 2; ++ks) {
;     const int tb = ks * 32 + 8 * (lane >> 4);
; #pragma unroll
;     for (int nf = 0; nf < 2; ++nf)
;       vb[ks][nf] = *(const bf16x8*)(vT + (size_t)(ci.h * 128 + 32 * w + nf * 16 + (lane & 15)) * LDT + ci.r0 + tb);
; #pragma unroll
;     for (int mf = 0; mf < 4; ++mf)
;       kr[ks][mf] = *(const bf16x8*)(kT + (size_t)(ci.h * 64 + mf * 16 + (lane & 15)) * LDT + ci.r0 + tb);
;   }
.LBB0_545:
	s_or_b64 exec, exec, s[0:1]
	s_waitcnt vmcnt(1)
	v_and_b32_e32 v8, 3, v1
	v_mov_b32_e32 v1, v0
	v_ashrrev_i32_e32 v53, 31, v52
	s_waitcnt lgkmcnt(1)
	v_ashrrev_i32_e32 v74, 6, v1
	v_lshrrev_b32_e32 v3, 1, v1
	v_and_b32_e32 v73, 24, v3
	v_lshlrev_b32_e32 v3, 5, v74
	s_waitcnt vmcnt(0) lgkmcnt(0)
	v_lshl_add_u32 v4, v8, 7, v3
	v_and_b32_e32 v65, 15, v1
	v_readlane_b32 s0, v194, 35
	v_or_b32_e32 v14, v4, v65
	s_waitcnt lgkmcnt(0)
	v_lshlrev_b64 v[4:5], 1, v[52:53]
	v_readlane_b32 s1, v194, 36
	v_lshlrev_b32_e32 v10, 1, v73
	v_mov_b32_e32 v11, v2
	v_lshl_add_u64 v[6:7], s[0:1], 0, v[4:5]
	v_readlane_b32 s0, v194, 55
	v_lshlrev_b32_e32 v58, 6, v8
	v_readlane_b32 s1, v194, 56
	v_lshl_add_u64 v[6:7], v[6:7], 0, v[10:11]
	v_or_b32_e32 v8, v58, v65
	v_lshl_add_u64 v[4:5], s[0:1], 0, v[4:5]
	v_mad_i64_i32 v[12:13], s[0:1], v14, s88, v[6:7]
	v_or_b32_e32 v14, 16, v14
	v_mul_u32_u24_e32 v8, 0x8980, v8
	v_mov_b32_e32 v9, v2
	v_mad_i64_i32 v[14:15], s[0:1], v14, s88, v[6:7]
	v_lshl_add_u64 v[4:5], v[4:5], 0, v[10:11]
	v_lshl_add_u64 v[16:17], v[4:5], 0, v[8:9]
	s_mov_b32 s0, 0x89000
	v_add_co_u32_e32 v18, vcc, s0, v16
	s_mov_b32 s0, 0x113000
	s_nop 0
	v_addc_co_u32_e32 v19, vcc, 0, v17, vcc
	v_add_co_u32_e32 v54, vcc, s0, v16
	s_mov_b32 s0, 0x19c000
	s_nop 0
	v_addc_co_u32_e32 v55, vcc, 0, v17, vcc
	v_add_co_u32_e32 v56, vcc, s0, v16
	v_mov_b32_e32 v67, v0
	s_nop 0
	v_addc_co_u32_e32 v57, vcc, 0, v17, vcc
	v_readlane_b32 s0, v194, 57
	v_readlane_b32 s1, v194, 58
	v_ashrrev_i32_e32 v210, 2, v0
	v_add_u32_e32 v208, v210, v52
	v_ashrrev_i32_e32 v209, 31, v208
	v_lshlrev_b64 v[208:209], 6, v[208:209]
	v_lshlrev_b32_e32 v210, 4, v0
	v_and_b32_e32 v210, 48, v210
	v_mov_b32_e32 v211, 0
	v_lshl_add_u64 v[208:209], s[0:1], 0, v[208:209]
	v_lshl_add_u64 v[208:209], v[208:209], 0, v[210:211]
	global_load_dwordx4 v[204:207], v[208:209], off
	global_load_dwordx4 v[28:31], v[12:13], off
	global_load_dwordx4 v[32:35], v[14:15], off
	global_load_dwordx4 v[48:51], v[16:17], off
	global_load_dwordx4 v[44:47], v[18:19], off offset:2048
	global_load_dwordx4 v[40:43], v[54:55], off
	global_load_dwordx4 v[36:39], v[56:57], off offset:2048
	global_load_dwordx4 v[4:7], v[12:13], off offset:64
	global_load_dwordx4 v[8:11], v[14:15], off offset:64
	global_load_dwordx4 v[24:27], v[16:17], off offset:64
	global_load_dwordx4 v[20:23], v[18:19], off offset:2112
	s_nop 0
	global_load_dwordx4 v[16:19], v[54:55], off offset:64
	global_load_dwordx4 v[12:15], v[56:57], off offset:2112
	v_readlane_b32 s0, v194, 57
	v_ashrrev_i32_e32 v59, 2, v67
	v_add_u32_e32 v52, v59, v52
	v_ashrrev_i32_e32 v53, 31, v52
	v_lshlrev_b64 v[52:53], 6, v[52:53]
	v_readlane_b32 s1, v194, 58
	v_lshlrev_b32_e32 v54, 4, v67
	v_and_b32_e32 v56, 48, v54
	v_lshl_add_u64 v[52:53], s[0:1], 0, v[52:53]
	v_mov_b32_e32 v57, v2
	v_lshl_add_u64 v[52:53], v[52:53], 0, v[56:57]
	s_barrier
	v_and_b32_e32 v75, 63, v67
	v_lshl_or_b32 v56, v59, 6, v56
	v_mov_b32_e32 v79, v2
	s_movk_i32 s0, 0x1000
	v_mov_b32_e32 v80, 0
	s_waitcnt vmcnt(12)
	ds_write_b128 v56, v[204:207]
	v_or_b32_e32 v52, v75, v58
	v_lshlrev_b32_e32 v78, 2, v52
	v_lshl_add_u64 v[76:77], s[68:69], 0, v[78:79]
	v_add_co_u32_e32 v54, vcc, s0, v76
	s_movk_i32 s0, 0x2000
	s_nop 0
	v_addc_co_u32_e32 v55, vcc, 0, v77, vcc
	v_add_co_u32_e32 v70, vcc, s0, v76
	global_load_dword v62, v78, s[68:69]
	global_load_dword v68, v78, s[68:69] offset:1024
	global_load_dword v56, v78, s[68:69] offset:2048
	global_load_dword v52, v78, s[68:69] offset:3072
	v_addc_co_u32_e32 v71, vcc, 0, v77, vcc
	global_load_dword v63, v[70:71], off offset:-4096
	global_load_dword v69, v[54:55], off offset:1024
	global_load_dword v57, v[54:55], off offset:2048
	global_load_dword v53, v[54:55], off offset:3072
	global_load_dword v58, v[70:71], off
	global_load_dword v60, v[70:71], off offset:1024
	s_nop 0
	global_load_dword v54, v[70:71], off offset:2048
	s_nop 0
	global_load_dword v70, v[70:71], off offset:3072
	s_movk_i32 s0, 0x3000
	v_add_co_u32_e32 v76, vcc, s0, v76
	s_nop 1
	v_addc_co_u32_e32 v77, vcc, 0, v77, vcc
	global_load_dword v59, v[76:77], off
	global_load_dword v61, v[76:77], off offset:1024
	global_load_dword v55, v[76:77], off offset:2048
	global_load_dword v71, v[76:77], off offset:3072
	v_ashrrev_i32_e32 v76, 6, v67
	global_load_dword v78, v78, s[70:71]
	v_lshlrev_b32_e32 v81, 4, v76
	v_cmp_lt_i32_e32 vcc, v81, v72
	v_mov_b32_e32 v77, 0
	s_waitcnt lgkmcnt(0)
	s_barrier
	s_and_saveexec_b64 s[36:37], vcc
	s_cbranch_execz .LBB0_547
	v_lshlrev_b32_e32 v77, 10, v76
	ds_read_b128 v[82:85], v77
	ds_read_b128 v[86:89], v77 offset:16
	ds_read_b128 v[106:109], v77 offset:32
	ds_read_b128 v[110:113], v77 offset:48
	s_mov_b32 s0, 0xbfb8aa3b
	s_waitcnt lgkmcnt(3)
	v_mov_b32_e32 v90, v82
	s_waitcnt lgkmcnt(2)
	v_mov_b32_e32 v91, v86
	v_mov_b32_e32 v86, v83
	s_waitcnt vmcnt(11)
	v_pk_mul_f32 v[82:83], v[68:69], v[86:87]
	v_mov_b32_e32 v86, v84
	v_pk_fma_f32 v[82:83], v[62:63], v[90:91], v[82:83]
	v_mov_b32_e32 v87, v88
	s_waitcnt vmcnt(10)
	v_pk_fma_f32 v[82:83], v[56:57], v[86:87], v[82:83]
	v_mov_b32_e32 v88, v85
	s_waitcnt vmcnt(9)
	v_pk_fma_f32 v[82:83], v[52:53], v[88:89], v[82:83]
	s_waitcnt vmcnt(0)
	v_add_f32_e32 v77, v78, v82
	v_add_f32_e32 v77, v77, v83
	s_waitcnt lgkmcnt(0)
	v_mov_b32_e32 v83, v110
	v_mov_b32_e32 v110, v107
	v_mov_b32_e32 v82, v106
	v_pk_mul_f32 v[84:85], v[60:61], v[110:111]
	s_nop 0
	v_pk_fma_f32 v[82:83], v[58:59], v[82:83], v[84:85]
	v_mov_b32_e32 v84, v108
	v_mov_b32_e32 v85, v112
	v_pk_fma_f32 v[82:83], v[54:55], v[84:85], v[82:83]
	v_mov_b32_e32 v112, v109
	v_pk_fma_f32 v[82:83], v[70:71], v[112:113], v[82:83]
	s_nop 0
	v_add_f32_e32 v77, v77, v82
	v_add_f32_e32 v77, v77, v83
	v_mul_f32_e64 v79, |v77|, s0
	v_exp_f32_e32 v79, v79
	s_mov_b32 s0, 0x3f317217
	v_min_f32_e32 v77, 0, v77
	v_add_f32_e32 v79, 1.0, v79
	v_cmp_gt_f32_e32 vcc, s33, v79
	s_nop 1
	v_cndmask_b32_e64 v82, 0, 32, vcc
	v_ldexp_f32 v79, v79, v82
	v_log_f32_e32 v79, v79
	s_nop 0
	v_mul_f32_e32 v82, 0x3f317217, v79
	v_fma_f32 v82, v79, s0, -v82
	v_fmac_f32_e32 v82, 0x3377d1cf, v79
	s_mov_b32 s0, 0x7f800000
	v_fmac_f32_e32 v82, 0x3f317217, v79
	v_cmp_lt_f32_e64 s[34:35], |v79|, s0
	s_mov_b32 s0, 0x3d800000
	s_nop 0
	v_cndmask_b32_e64 v79, v79, v82, s[34:35]
	v_cndmask_b32_e32 v82, 0, v126, vcc
	v_sub_f32_e32 v79, v79, v82
	v_sub_f32_e32 v77, v77, v79
	v_fma_f32 v77, v77, s0, 0

; DEVINL void tr_tile(const Params& p, char* smem, int kind, int nt, int kt) {
;     ...
;   if (kind == 0) {
;     src = p.w_in; ld = DIN; ksc = p.g_pre_mix; dst = (u16*)(p.ws + OFF_W1T);
;     if (n < 256) { col = n; cs = 0.125f; }
;     else if (n < 1536) col = n;
;     else if (n < 2048) col = 1552 + (n - 1536);
;     else if (n < 2064) col = 1536 + (n - 2048);
;     else { valid = false; col = 0; }
;     ...
;   __syncthreads();
; #pragma unroll 4
;   for (int i = 0; i < 16; ++i) {
;     int k = kq * 16 + i;
;     float v = valid ? src[(size_t)(k0 + k) * ld + col] : 0.f;
;     if (ksc) v *= ksc[k0 + k];
;     if (kind == 2 && (k0 + k) >= 512) v *= p.s5_norm[k0 + k - 512];
;     T[k * 65 + nl] = v * cs;
.LBB0_1526:
	s_or_b64 exec, exec, s[34:35]
	s_waitcnt vmcnt(0) lgkmcnt(0)
	v_lshlrev_b32_e32 v4, 4, v10
	v_sub_u32_e32 v4, v1, v4
	v_ashrrev_i32_e32 v14, 2, v15
	v_lshlrev_b32_e32 v4, 6, v4
	v_and_b32_e32 v12, -16, v14
	v_ashrrev_i32_e32 v5, 31, v4
	v_ashrrev_i32_e32 v13, 31, v12
	v_lshl_add_u64 v[6:7], v[12:13], 0, v[4:5]
	v_lshrrev_b32_e32 v13, 4, v14
	s_movk_i32 s0, 0x1040
	v_mul_lo_u32 v13, v13, s0
	v_ashrrev_i32_e32 v9, 31, v8
	v_lshl_add_u32 v17, v11, 2, v13
	v_lshl_add_u32 v11, v1, 6, v12
	v_lshlrev_b32_e32 v10, 10, v10
	v_sub_u32_e32 v10, v11, v10
	v_lshlrev_b64 v[8:9], 2, v[8:9]
	s_movk_i32 s0, 0x2040
	v_mad_i64_i32 v[8:9], s[0:1], v10, s0, v[8:9]
	v_readlane_b32 s0, v192, 35
	v_ashrrev_i32_e32 v11, 31, v10
	v_readlane_b32 s1, v192, 36
	v_lshl_add_u64 v[6:7], v[6:7], 2, s[64:65]
	v_lshl_add_u64 v[10:11], v[10:11], 2, s[64:65]
	v_lshl_add_u64 v[8:9], s[0:1], 0, v[8:9]
	s_mov_b64 s[42:43], 0
	s_barrier
	s_and_saveexec_b64 s[0:1], s[38:39]
	s_mov_b32 s100, 0xffff9f40
	s_mov_b32 s101, -1
	v_lshl_add_u64 v[206:207], v[8:9], 0, s[100:101]
	s_mov_b64 s[100:101], 0x2040
	global_load_dword v204, v[206:207], off
	v_lshl_add_u64 v[206:207], v[206:207], 0, s[100:101]
	global_load_dword v204, v[206:207], off
	v_lshl_add_u64 v[206:207], v[206:207], 0, s[100:101]
	global_load_dword v204, v[206:207], off
	v_lshl_add_u64 v[206:207], v[206:207], 0, s[100:101]
	global_load_dword v204, v[206:207], off
	v_lshl_add_u64 v[206:207], v[206:207], 0, s[100:101]
	global_load_dword v204, v[206:207], off
	v_lshl_add_u64 v[206:207], v[206:207], 0, s[100:101]
	global_load_dword v204, v[206:207], off
	v_lshl_add_u64 v[206:207], v[206:207], 0, s[100:101]
	global_load_dword v204, v[206:207], off
	v_lshl_add_u64 v[206:207], v[206:207], 0, s[100:101]
	global_load_dword v204, v[206:207], off
	v_lshl_add_u64 v[206:207], v[206:207], 0, s[100:101]
	global_load_dword v204, v[206:207], off
	v_lshl_add_u64 v[206:207], v[206:207], 0, s[100:101]
	global_load_dword v204, v[206:207], off
	v_lshl_add_u64 v[206:207], v[206:207], 0, s[100:101]
	global_load_dword v204, v[206:207], off
	v_lshl_add_u64 v[206:207], v[206:207], 0, s[100:101]
	global_load_dword v204, v[206:207], off
	v_lshl_add_u64 v[206:207], v[206:207], 0, s[100:101]
	global_load_dword v204, v[206:207], off
	v_lshl_add_u64 v[206:207], v[206:207], 0, s[100:101]
	global_load_dword v204, v[206:207], off
	v_lshl_add_u64 v[206:207], v[206:207], 0, s[100:101]
	global_load_dword v204, v[206:207], off
	v_lshl_add_u64 v[206:207], v[206:207], 0, s[100:101]
	global_load_dword v204, v[206:207], off
	s_mov_b64 exec, s[0:1]
	s_branch .LBB0_1528
